# rope in place (q_n / k_s / k_w slots): all 24 quads of a token row fetched together instead of one slot per trip
# speedup vs baseline: 1.0057x; 1.0057x over previous
.LBB0_666:
	v_ashrrev_i32_e32 v1, 31, v0
	v_lshl_add_u64 v[4:5], v[0:1], 2, s[8:9]
	global_load_dword v1, v[4:5], off
	s_movk_i32 s19, 0x100
	s_mov_b32 s20, s15
	s_waitcnt vmcnt(0)
	v_cvt_f32_i32_e32 v1, v1
	v_cvt_f64_f32_e32 v[4:5], v1
	v_mul_f32_e32 v8, 0x3e4693b0, v1
	v_mul_f32_e32 v10, 0x3d1a08c8, v1
	v_mul_f32_e32 v12, 0x3beef74e, v1
	v_mul_f32_e32 v14, 0x3ab95d22, v1
	v_mul_f32_e32 v16, 0x398fc8f7, v1
	v_mul_f32_e32 v18, 0x385f10c4, v1
	v_mul_f32_e32 v1, 0x372d07a7, v1
	v_mul_f64 v[6:7], v[4:5], s[12:13]
	v_cvt_f64_f32_e32 v[8:9], v8
	v_cvt_f64_f32_e32 v[10:11], v10
	v_cvt_f64_f32_e32 v[12:13], v12
	v_cvt_f64_f32_e32 v[14:15], v14
	v_cvt_f64_f32_e32 v[16:17], v16
	v_cvt_f64_f32_e32 v[18:19], v18
	v_cvt_f64_f32_e32 v[20:21], v1
	v_rndne_f64_e32 v[6:7], v[6:7]
	v_mul_f64 v[22:23], v[8:9], s[12:13]
	v_mul_f64 v[24:25], v[10:11], s[12:13]
	v_mul_f64 v[26:27], v[12:13], s[12:13]
	v_mul_f64 v[28:29], v[14:15], s[12:13]
	v_mul_f64 v[30:31], v[16:17], s[12:13]
	v_mul_f64 v[32:33], v[18:19], s[12:13]
	v_mul_f64 v[34:35], v[20:21], s[12:13]
	v_fma_f64 v[4:5], v[4:5], s[12:13], -v[6:7]
	v_rndne_f64_e32 v[6:7], v[22:23]
	v_rndne_f64_e32 v[22:23], v[24:25]
	v_rndne_f64_e32 v[24:25], v[26:27]
	v_rndne_f64_e32 v[26:27], v[28:29]
	v_rndne_f64_e32 v[28:29], v[30:31]
	v_rndne_f64_e32 v[30:31], v[32:33]
	v_rndne_f64_e32 v[32:33], v[34:35]
	v_cvt_f32_f64_e32 v1, v[4:5]
	v_fma_f64 v[8:9], v[8:9], s[12:13], -v[6:7]
	v_fma_f64 v[10:11], v[10:11], s[12:13], -v[22:23]
	v_fma_f64 v[12:13], v[12:13], s[12:13], -v[24:25]
	v_fma_f64 v[14:15], v[14:15], s[12:13], -v[26:27]
	v_fma_f64 v[16:17], v[16:17], s[12:13], -v[28:29]
	v_fma_f64 v[18:19], v[18:19], s[12:13], -v[30:31]
	v_fma_f64 v[20:21], v[20:21], s[12:13], -v[32:33]
	v_sin_f32_e32 v4, v1
	v_cos_f32_e32 v6, v1
	v_cvt_f32_f64_e32 v1, v[8:9]
	v_cvt_f32_f64_e32 v9, v[10:11]
	v_cvt_f32_f64_e32 v11, v[12:13]
	v_cvt_f32_f64_e32 v13, v[14:15]
	v_cvt_f32_f64_e32 v15, v[16:17]
	v_cvt_f32_f64_e32 v17, v[18:19]
	v_cvt_f32_f64_e32 v19, v[20:21]
	v_sin_f32_e32 v5, v1
	v_cos_f32_e32 v7, v1
	v_sin_f32_e32 v8, v9
	v_cos_f32_e32 v10, v9
	v_sin_f32_e32 v9, v11
	v_cos_f32_e32 v11, v11
	v_sin_f32_e32 v12, v13
	v_cos_f32_e32 v14, v13
	v_sin_f32_e32 v13, v15
	v_cos_f32_e32 v15, v15
	v_sin_f32_e32 v16, v17
	v_cos_f32_e32 v18, v17
	v_sin_f32_e32 v17, v19
	v_cos_f32_e32 v19, v19
	v_mad_i64_i32 v[20:21], s[16:17], v0, s3, v[2:3]
	global_load_dwordx4 v[48:51], v[20:21], off
	global_load_dwordx4 v[52:55], v[20:21], off offset:16
	global_load_dwordx4 v[56:59], v[20:21], off offset:128
	global_load_dwordx4 v[60:63], v[20:21], off offset:144
	global_load_dwordx4 v[64:67], v[20:21], off offset:256
	global_load_dwordx4 v[68:71], v[20:21], off offset:272
	global_load_dwordx4 v[72:75], v[20:21], off offset:384
	global_load_dwordx4 v[76:79], v[20:21], off offset:400
	global_load_dwordx4 v[80:83], v[20:21], off offset:512
	global_load_dwordx4 v[84:87], v[20:21], off offset:528
	global_load_dwordx4 v[88:91], v[20:21], off offset:640
	global_load_dwordx4 v[92:95], v[20:21], off offset:656
	global_load_dwordx4 v[96:99], v[20:21], off offset:768
	global_load_dwordx4 v[100:103], v[20:21], off offset:784
	global_load_dwordx4 v[104:107], v[20:21], off offset:896
	global_load_dwordx4 v[108:111], v[20:21], off offset:912
	global_load_dwordx4 v[112:115], v[20:21], off offset:1536
	global_load_dwordx4 v[116:119], v[20:21], off offset:1552
	global_load_dwordx4 v[120:123], v[20:21], off offset:1664
	global_load_dwordx4 v[124:127], v[20:21], off offset:1680
	global_load_dwordx4 v[128:131], v[20:21], off offset:2048
	global_load_dwordx4 v[132:135], v[20:21], off offset:2064
	global_load_dwordx4 v[136:139], v[20:21], off offset:2176
	global_load_dwordx4 v[140:143], v[20:21], off offset:2192
	s_waitcnt vmcnt(22)
	v_lshlrev_b32_e32 v32, 16, v48
	v_lshlrev_b32_e32 v34, 16, v52
	v_and_b32_e32 v35, 0xffff0000, v52
	v_lshlrev_b32_e32 v52, 16, v53
	v_and_b32_e32 v53, 0xffff0000, v53
	v_lshlrev_b32_e32 v38, 16, v54
	v_and_b32_e32 v39, 0xffff0000, v54
	v_lshlrev_b32_e32 v54, 16, v55
	v_and_b32_e32 v55, 0xffff0000, v55
	v_and_b32_e32 v33, 0xffff0000, v48
	v_lshlrev_b32_e32 v48, 16, v49
	v_and_b32_e32 v49, 0xffff0000, v49
	v_lshlrev_b32_e32 v36, 16, v50
	v_and_b32_e32 v37, 0xffff0000, v50
	v_lshlrev_b32_e32 v50, 16, v51
	v_and_b32_e32 v51, 0xffff0000, v51
	v_pk_mul_f32 v[40:41], v[6:7], v[34:35]
	v_pk_mul_f32 v[34:35], v[4:5], v[34:35]
	v_pk_mul_f32 v[42:43], v[10:11], v[52:53]
	v_pk_mul_f32 v[52:53], v[8:9], v[52:53]
	v_pk_mul_f32 v[44:45], v[14:15], v[38:39]
	v_pk_mul_f32 v[38:39], v[12:13], v[38:39]
	v_pk_mul_f32 v[46:47], v[18:19], v[54:55]
	v_pk_mul_f32 v[54:55], v[16:17], v[54:55]
	v_pk_fma_f32 v[40:41], v[4:5], v[32:33], v[40:41]
	v_pk_fma_f32 v[32:33], v[6:7], v[32:33], v[34:35] neg_lo:[0,0,1] neg_hi:[0,0,1]
	v_pk_fma_f32 v[34:35], v[8:9], v[48:49], v[42:43]
	v_pk_fma_f32 v[52:53], v[10:11], v[48:49], v[52:53] neg_lo:[0,0,1] neg_hi:[0,0,1]
	v_pk_fma_f32 v[42:43], v[12:13], v[36:37], v[44:45]
	v_pk_fma_f32 v[36:37], v[14:15], v[36:37], v[38:39] neg_lo:[0,0,1] neg_hi:[0,0,1]
	v_pk_fma_f32 v[54:55], v[18:19], v[50:51], v[54:55] neg_lo:[0,0,1] neg_hi:[0,0,1]
	v_pk_fma_f32 v[38:39], v[16:17], v[50:51], v[46:47]
	v_cvt_pk_bf16_f32 v48, v32, v33
	v_cvt_pk_bf16_f32 v49, v52, v53
	v_cvt_pk_bf16_f32 v50, v36, v37
	v_cvt_pk_bf16_f32 v51, v54, v55
	v_cvt_pk_bf16_f32 v52, v40, v41
	v_cvt_pk_bf16_f32 v53, v34, v35
	v_cvt_pk_bf16_f32 v54, v42, v43
	v_cvt_pk_bf16_f32 v55, v38, v39
	global_store_dwordx4 v[20:21], v[48:51], off
	global_store_dwordx4 v[20:21], v[52:55], off offset:16
	s_waitcnt vmcnt(22)
	v_lshlrev_b32_e32 v32, 16, v56
	v_lshlrev_b32_e32 v34, 16, v60
	v_and_b32_e32 v35, 0xffff0000, v60
	v_lshlrev_b32_e32 v60, 16, v61
	v_and_b32_e32 v61, 0xffff0000, v61
	v_lshlrev_b32_e32 v38, 16, v62
	v_and_b32_e32 v39, 0xffff0000, v62
	v_lshlrev_b32_e32 v62, 16, v63
	v_and_b32_e32 v63, 0xffff0000, v63
	v_and_b32_e32 v33, 0xffff0000, v56
	v_lshlrev_b32_e32 v56, 16, v57
	v_and_b32_e32 v57, 0xffff0000, v57
	v_lshlrev_b32_e32 v36, 16, v58
	v_and_b32_e32 v37, 0xffff0000, v58
	v_lshlrev_b32_e32 v58, 16, v59
	v_and_b32_e32 v59, 0xffff0000, v59
	v_pk_mul_f32 v[40:41], v[6:7], v[34:35]
	v_pk_mul_f32 v[34:35], v[4:5], v[34:35]
	v_pk_mul_f32 v[42:43], v[10:11], v[60:61]
	v_pk_mul_f32 v[60:61], v[8:9], v[60:61]
	v_pk_mul_f32 v[44:45], v[14:15], v[38:39]
	v_pk_mul_f32 v[38:39], v[12:13], v[38:39]
	v_pk_mul_f32 v[46:47], v[18:19], v[62:63]
	v_pk_mul_f32 v[62:63], v[16:17], v[62:63]
	v_pk_fma_f32 v[40:41], v[4:5], v[32:33], v[40:41]
	v_pk_fma_f32 v[32:33], v[6:7], v[32:33], v[34:35] neg_lo:[0,0,1] neg_hi:[0,0,1]
	v_pk_fma_f32 v[34:35], v[8:9], v[56:57], v[42:43]
	v_pk_fma_f32 v[60:61], v[10:11], v[56:57], v[60:61] neg_lo:[0,0,1] neg_hi:[0,0,1]
	v_pk_fma_f32 v[42:43], v[12:13], v[36:37], v[44:45]
	v_pk_fma_f32 v[36:37], v[14:15], v[36:37], v[38:39] neg_lo:[0,0,1] neg_hi:[0,0,1]
	v_pk_fma_f32 v[62:63], v[18:19], v[58:59], v[62:63] neg_lo:[0,0,1] neg_hi:[0,0,1]
	v_pk_fma_f32 v[38:39], v[16:17], v[58:59], v[46:47]
	v_cvt_pk_bf16_f32 v56, v32, v33
	v_cvt_pk_bf16_f32 v57, v60, v61
	v_cvt_pk_bf16_f32 v58, v36, v37
	v_cvt_pk_bf16_f32 v59, v62, v63
	v_cvt_pk_bf16_f32 v60, v40, v41
	v_cvt_pk_bf16_f32 v61, v34, v35
	v_cvt_pk_bf16_f32 v62, v42, v43
	v_cvt_pk_bf16_f32 v63, v38, v39
	global_store_dwordx4 v[20:21], v[56:59], off offset:128
	global_store_dwordx4 v[20:21], v[60:63], off offset:144
	s_waitcnt vmcnt(22)
	v_lshlrev_b32_e32 v32, 16, v64
	v_lshlrev_b32_e32 v34, 16, v68
	v_and_b32_e32 v35, 0xffff0000, v68
	v_lshlrev_b32_e32 v68, 16, v69
	v_and_b32_e32 v69, 0xffff0000, v69
	v_lshlrev_b32_e32 v38, 16, v70
	v_and_b32_e32 v39, 0xffff0000, v70
	v_lshlrev_b32_e32 v70, 16, v71
	v_and_b32_e32 v71, 0xffff0000, v71
	v_and_b32_e32 v33, 0xffff0000, v64
	v_lshlrev_b32_e32 v64, 16, v65
	v_and_b32_e32 v65, 0xffff0000, v65
	v_lshlrev_b32_e32 v36, 16, v66
	v_and_b32_e32 v37, 0xffff0000, v66
	v_lshlrev_b32_e32 v66, 16, v67
	v_and_b32_e32 v67, 0xffff0000, v67
	v_pk_mul_f32 v[40:41], v[6:7], v[34:35]
	v_pk_mul_f32 v[34:35], v[4:5], v[34:35]
	v_pk_mul_f32 v[42:43], v[10:11], v[68:69]
	v_pk_mul_f32 v[68:69], v[8:9], v[68:69]
	v_pk_mul_f32 v[44:45], v[14:15], v[38:39]
	v_pk_mul_f32 v[38:39], v[12:13], v[38:39]
	v_pk_mul_f32 v[46:47], v[18:19], v[70:71]
	v_pk_mul_f32 v[70:71], v[16:17], v[70:71]
	v_pk_fma_f32 v[40:41], v[4:5], v[32:33], v[40:41]
	v_pk_fma_f32 v[32:33], v[6:7], v[32:33], v[34:35] neg_lo:[0,0,1] neg_hi:[0,0,1]
	v_pk_fma_f32 v[34:35], v[8:9], v[64:65], v[42:43]
	v_pk_fma_f32 v[68:69], v[10:11], v[64:65], v[68:69] neg_lo:[0,0,1] neg_hi:[0,0,1]
	v_pk_fma_f32 v[42:43], v[12:13], v[36:37], v[44:45]
	v_pk_fma_f32 v[36:37], v[14:15], v[36:37], v[38:39] neg_lo:[0,0,1] neg_hi:[0,0,1]
	v_pk_fma_f32 v[70:71], v[18:19], v[66:67], v[70:71] neg_lo:[0,0,1] neg_hi:[0,0,1]
	v_pk_fma_f32 v[38:39], v[16:17], v[66:67], v[46:47]
	v_cvt_pk_bf16_f32 v64, v32, v33
	v_cvt_pk_bf16_f32 v65, v68, v69
	v_cvt_pk_bf16_f32 v66, v36, v37
	v_cvt_pk_bf16_f32 v67, v70, v71
	v_cvt_pk_bf16_f32 v68, v40, v41
	v_cvt_pk_bf16_f32 v69, v34, v35
	v_cvt_pk_bf16_f32 v70, v42, v43
	v_cvt_pk_bf16_f32 v71, v38, v39
	global_store_dwordx4 v[20:21], v[64:67], off offset:256
	global_store_dwordx4 v[20:21], v[68:71], off offset:272
	s_waitcnt vmcnt(22)
	v_lshlrev_b32_e32 v32, 16, v72
	v_lshlrev_b32_e32 v34, 16, v76
	v_and_b32_e32 v35, 0xffff0000, v76
	v_lshlrev_b32_e32 v76, 16, v77
	v_and_b32_e32 v77, 0xffff0000, v77
	v_lshlrev_b32_e32 v38, 16, v78
	v_and_b32_e32 v39, 0xffff0000, v78
	v_lshlrev_b32_e32 v78, 16, v79
	v_and_b32_e32 v79, 0xffff0000, v79
	v_and_b32_e32 v33, 0xffff0000, v72
	v_lshlrev_b32_e32 v72, 16, v73
	v_and_b32_e32 v73, 0xffff0000, v73
	v_lshlrev_b32_e32 v36, 16, v74
	v_and_b32_e32 v37, 0xffff0000, v74
	v_lshlrev_b32_e32 v74, 16, v75
	v_and_b32_e32 v75, 0xffff0000, v75
	v_pk_mul_f32 v[40:41], v[6:7], v[34:35]
	v_pk_mul_f32 v[34:35], v[4:5], v[34:35]
	v_pk_mul_f32 v[42:43], v[10:11], v[76:77]
	v_pk_mul_f32 v[76:77], v[8:9], v[76:77]
	v_pk_mul_f32 v[44:45], v[14:15], v[38:39]
	v_pk_mul_f32 v[38:39], v[12:13], v[38:39]
	v_pk_mul_f32 v[46:47], v[18:19], v[78:79]
	v_pk_mul_f32 v[78:79], v[16:17], v[78:79]
	v_pk_fma_f32 v[40:41], v[4:5], v[32:33], v[40:41]
	v_pk_fma_f32 v[32:33], v[6:7], v[32:33], v[34:35] neg_lo:[0,0,1] neg_hi:[0,0,1]
	v_pk_fma_f32 v[34:35], v[8:9], v[72:73], v[42:43]
	v_pk_fma_f32 v[76:77], v[10:11], v[72:73], v[76:77] neg_lo:[0,0,1] neg_hi:[0,0,1]
	v_pk_fma_f32 v[42:43], v[12:13], v[36:37], v[44:45]
	v_pk_fma_f32 v[36:37], v[14:15], v[36:37], v[38:39] neg_lo:[0,0,1] neg_hi:[0,0,1]
	v_pk_fma_f32 v[78:79], v[18:19], v[74:75], v[78:79] neg_lo:[0,0,1] neg_hi:[0,0,1]
	v_pk_fma_f32 v[38:39], v[16:17], v[74:75], v[46:47]
	v_cvt_pk_bf16_f32 v72, v32, v33
	v_cvt_pk_bf16_f32 v73, v76, v77
	v_cvt_pk_bf16_f32 v74, v36, v37
	v_cvt_pk_bf16_f32 v75, v78, v79
	v_cvt_pk_bf16_f32 v76, v40, v41
	v_cvt_pk_bf16_f32 v77, v34, v35
	v_cvt_pk_bf16_f32 v78, v42, v43
	v_cvt_pk_bf16_f32 v79, v38, v39
	global_store_dwordx4 v[20:21], v[72:75], off offset:384
	global_store_dwordx4 v[20:21], v[76:79], off offset:400
	s_waitcnt vmcnt(22)
	v_lshlrev_b32_e32 v32, 16, v80
	v_lshlrev_b32_e32 v34, 16, v84
	v_and_b32_e32 v35, 0xffff0000, v84
	v_lshlrev_b32_e32 v84, 16, v85
	v_and_b32_e32 v85, 0xffff0000, v85
	v_lshlrev_b32_e32 v38, 16, v86
	v_and_b32_e32 v39, 0xffff0000, v86
	v_lshlrev_b32_e32 v86, 16, v87
	v_and_b32_e32 v87, 0xffff0000, v87
	v_and_b32_e32 v33, 0xffff0000, v80
	v_lshlrev_b32_e32 v80, 16, v81
	v_and_b32_e32 v81, 0xffff0000, v81
	v_lshlrev_b32_e32 v36, 16, v82
	v_and_b32_e32 v37, 0xffff0000, v82
	v_lshlrev_b32_e32 v82, 16, v83
	v_and_b32_e32 v83, 0xffff0000, v83
	v_pk_mul_f32 v[40:41], v[6:7], v[34:35]
	v_pk_mul_f32 v[34:35], v[4:5], v[34:35]
	v_pk_mul_f32 v[42:43], v[10:11], v[84:85]
	v_pk_mul_f32 v[84:85], v[8:9], v[84:85]
	v_pk_mul_f32 v[44:45], v[14:15], v[38:39]
	v_pk_mul_f32 v[38:39], v[12:13], v[38:39]
	v_pk_mul_f32 v[46:47], v[18:19], v[86:87]
	v_pk_mul_f32 v[86:87], v[16:17], v[86:87]
	v_pk_fma_f32 v[40:41], v[4:5], v[32:33], v[40:41]
	v_pk_fma_f32 v[32:33], v[6:7], v[32:33], v[34:35] neg_lo:[0,0,1] neg_hi:[0,0,1]
	v_pk_fma_f32 v[34:35], v[8:9], v[80:81], v[42:43]
	v_pk_fma_f32 v[84:85], v[10:11], v[80:81], v[84:85] neg_lo:[0,0,1] neg_hi:[0,0,1]
	v_pk_fma_f32 v[42:43], v[12:13], v[36:37], v[44:45]
	v_pk_fma_f32 v[36:37], v[14:15], v[36:37], v[38:39] neg_lo:[0,0,1] neg_hi:[0,0,1]
	v_pk_fma_f32 v[86:87], v[18:19], v[82:83], v[86:87] neg_lo:[0,0,1] neg_hi:[0,0,1]
	v_pk_fma_f32 v[38:39], v[16:17], v[82:83], v[46:47]
	v_cvt_pk_bf16_f32 v80, v32, v33
	v_cvt_pk_bf16_f32 v81, v84, v85
	v_cvt_pk_bf16_f32 v82, v36, v37
	v_cvt_pk_bf16_f32 v83, v86, v87
	v_cvt_pk_bf16_f32 v84, v40, v41
	v_cvt_pk_bf16_f32 v85, v34, v35
	v_cvt_pk_bf16_f32 v86, v42, v43
	v_cvt_pk_bf16_f32 v87, v38, v39
	global_store_dwordx4 v[20:21], v[80:83], off offset:512
	global_store_dwordx4 v[20:21], v[84:87], off offset:528
	s_waitcnt vmcnt(22)
	v_lshlrev_b32_e32 v32, 16, v88
	v_lshlrev_b32_e32 v34, 16, v92
	v_and_b32_e32 v35, 0xffff0000, v92
	v_lshlrev_b32_e32 v92, 16, v93
	v_and_b32_e32 v93, 0xffff0000, v93
	v_lshlrev_b32_e32 v38, 16, v94
	v_and_b32_e32 v39, 0xffff0000, v94
	v_lshlrev_b32_e32 v94, 16, v95
	v_and_b32_e32 v95, 0xffff0000, v95
	v_and_b32_e32 v33, 0xffff0000, v88
	v_lshlrev_b32_e32 v88, 16, v89
	v_and_b32_e32 v89, 0xffff0000, v89
	v_lshlrev_b32_e32 v36, 16, v90
	v_and_b32_e32 v37, 0xffff0000, v90
	v_lshlrev_b32_e32 v90, 16, v91
	v_and_b32_e32 v91, 0xffff0000, v91
	v_pk_mul_f32 v[40:41], v[6:7], v[34:35]
	v_pk_mul_f32 v[34:35], v[4:5], v[34:35]
	v_pk_mul_f32 v[42:43], v[10:11], v[92:93]
	v_pk_mul_f32 v[92:93], v[8:9], v[92:93]
	v_pk_mul_f32 v[44:45], v[14:15], v[38:39]
	v_pk_mul_f32 v[38:39], v[12:13], v[38:39]
	v_pk_mul_f32 v[46:47], v[18:19], v[94:95]
	v_pk_mul_f32 v[94:95], v[16:17], v[94:95]
	v_pk_fma_f32 v[40:41], v[4:5], v[32:33], v[40:41]
	v_pk_fma_f32 v[32:33], v[6:7], v[32:33], v[34:35] neg_lo:[0,0,1] neg_hi:[0,0,1]
	v_pk_fma_f32 v[34:35], v[8:9], v[88:89], v[42:43]
	v_pk_fma_f32 v[92:93], v[10:11], v[88:89], v[92:93] neg_lo:[0,0,1] neg_hi:[0,0,1]
	v_pk_fma_f32 v[42:43], v[12:13], v[36:37], v[44:45]
	v_pk_fma_f32 v[36:37], v[14:15], v[36:37], v[38:39] neg_lo:[0,0,1] neg_hi:[0,0,1]
	v_pk_fma_f32 v[94:95], v[18:19], v[90:91], v[94:95] neg_lo:[0,0,1] neg_hi:[0,0,1]
	v_pk_fma_f32 v[38:39], v[16:17], v[90:91], v[46:47]
	v_cvt_pk_bf16_f32 v88, v32, v33
	v_cvt_pk_bf16_f32 v89, v92, v93
	v_cvt_pk_bf16_f32 v90, v36, v37
	v_cvt_pk_bf16_f32 v91, v94, v95
	v_cvt_pk_bf16_f32 v92, v40, v41
	v_cvt_pk_bf16_f32 v93, v34, v35
	v_cvt_pk_bf16_f32 v94, v42, v43
	v_cvt_pk_bf16_f32 v95, v38, v39
	global_store_dwordx4 v[20:21], v[88:91], off offset:640
	global_store_dwordx4 v[20:21], v[92:95], off offset:656
	s_waitcnt vmcnt(22)
	v_lshlrev_b32_e32 v32, 16, v96
	v_lshlrev_b32_e32 v34, 16, v100
	v_and_b32_e32 v35, 0xffff0000, v100
	v_lshlrev_b32_e32 v100, 16, v101
	v_and_b32_e32 v101, 0xffff0000, v101
	v_lshlrev_b32_e32 v38, 16, v102
	v_and_b32_e32 v39, 0xffff0000, v102
	v_lshlrev_b32_e32 v102, 16, v103
	v_and_b32_e32 v103, 0xffff0000, v103
	v_and_b32_e32 v33, 0xffff0000, v96
	v_lshlrev_b32_e32 v96, 16, v97
	v_and_b32_e32 v97, 0xffff0000, v97
	v_lshlrev_b32_e32 v36, 16, v98
	v_and_b32_e32 v37, 0xffff0000, v98
	v_lshlrev_b32_e32 v98, 16, v99
	v_and_b32_e32 v99, 0xffff0000, v99
	v_pk_mul_f32 v[40:41], v[6:7], v[34:35]
	v_pk_mul_f32 v[34:35], v[4:5], v[34:35]
	v_pk_mul_f32 v[42:43], v[10:11], v[100:101]
	v_pk_mul_f32 v[100:101], v[8:9], v[100:101]
	v_pk_mul_f32 v[44:45], v[14:15], v[38:39]
	v_pk_mul_f32 v[38:39], v[12:13], v[38:39]
	v_pk_mul_f32 v[46:47], v[18:19], v[102:103]
	v_pk_mul_f32 v[102:103], v[16:17], v[102:103]
	v_pk_fma_f32 v[40:41], v[4:5], v[32:33], v[40:41]
	v_pk_fma_f32 v[32:33], v[6:7], v[32:33], v[34:35] neg_lo:[0,0,1] neg_hi:[0,0,1]
	v_pk_fma_f32 v[34:35], v[8:9], v[96:97], v[42:43]
	v_pk_fma_f32 v[100:101], v[10:11], v[96:97], v[100:101] neg_lo:[0,0,1] neg_hi:[0,0,1]
	v_pk_fma_f32 v[42:43], v[12:13], v[36:37], v[44:45]
	v_pk_fma_f32 v[36:37], v[14:15], v[36:37], v[38:39] neg_lo:[0,0,1] neg_hi:[0,0,1]
	v_pk_fma_f32 v[102:103], v[18:19], v[98:99], v[102:103] neg_lo:[0,0,1] neg_hi:[0,0,1]
	v_pk_fma_f32 v[38:39], v[16:17], v[98:99], v[46:47]
	v_cvt_pk_bf16_f32 v96, v32, v33
	v_cvt_pk_bf16_f32 v97, v100, v101
	v_cvt_pk_bf16_f32 v98, v36, v37
	v_cvt_pk_bf16_f32 v99, v102, v103
	v_cvt_pk_bf16_f32 v100, v40, v41
	v_cvt_pk_bf16_f32 v101, v34, v35
	v_cvt_pk_bf16_f32 v102, v42, v43
	v_cvt_pk_bf16_f32 v103, v38, v39
	global_store_dwordx4 v[20:21], v[96:99], off offset:768
	global_store_dwordx4 v[20:21], v[100:103], off offset:784
	s_waitcnt vmcnt(22)
	v_lshlrev_b32_e32 v32, 16, v104
	v_lshlrev_b32_e32 v34, 16, v108
	v_and_b32_e32 v35, 0xffff0000, v108
	v_lshlrev_b32_e32 v108, 16, v109
	v_and_b32_e32 v109, 0xffff0000, v109
	v_lshlrev_b32_e32 v38, 16, v110
	v_and_b32_e32 v39, 0xffff0000, v110
	v_lshlrev_b32_e32 v110, 16, v111
	v_and_b32_e32 v111, 0xffff0000, v111
	v_and_b32_e32 v33, 0xffff0000, v104
	v_lshlrev_b32_e32 v104, 16, v105
	v_and_b32_e32 v105, 0xffff0000, v105
	v_lshlrev_b32_e32 v36, 16, v106
	v_and_b32_e32 v37, 0xffff0000, v106
	v_lshlrev_b32_e32 v106, 16, v107
	v_and_b32_e32 v107, 0xffff0000, v107
	v_pk_mul_f32 v[40:41], v[6:7], v[34:35]
	v_pk_mul_f32 v[34:35], v[4:5], v[34:35]
	v_pk_mul_f32 v[42:43], v[10:11], v[108:109]
	v_pk_mul_f32 v[108:109], v[8:9], v[108:109]
	v_pk_mul_f32 v[44:45], v[14:15], v[38:39]
	v_pk_mul_f32 v[38:39], v[12:13], v[38:39]
	v_pk_mul_f32 v[46:47], v[18:19], v[110:111]
	v_pk_mul_f32 v[110:111], v[16:17], v[110:111]
	v_pk_fma_f32 v[40:41], v[4:5], v[32:33], v[40:41]
	v_pk_fma_f32 v[32:33], v[6:7], v[32:33], v[34:35] neg_lo:[0,0,1] neg_hi:[0,0,1]
	v_pk_fma_f32 v[34:35], v[8:9], v[104:105], v[42:43]
	v_pk_fma_f32 v[108:109], v[10:11], v[104:105], v[108:109] neg_lo:[0,0,1] neg_hi:[0,0,1]
	v_pk_fma_f32 v[42:43], v[12:13], v[36:37], v[44:45]
	v_pk_fma_f32 v[36:37], v[14:15], v[36:37], v[38:39] neg_lo:[0,0,1] neg_hi:[0,0,1]
	v_pk_fma_f32 v[110:111], v[18:19], v[106:107], v[110:111] neg_lo:[0,0,1] neg_hi:[0,0,1]
	v_pk_fma_f32 v[38:39], v[16:17], v[106:107], v[46:47]
	v_cvt_pk_bf16_f32 v104, v32, v33
	v_cvt_pk_bf16_f32 v105, v108, v109
	v_cvt_pk_bf16_f32 v106, v36, v37
	v_cvt_pk_bf16_f32 v107, v110, v111
	v_cvt_pk_bf16_f32 v108, v40, v41
	v_cvt_pk_bf16_f32 v109, v34, v35
	v_cvt_pk_bf16_f32 v110, v42, v43
	v_cvt_pk_bf16_f32 v111, v38, v39
	global_store_dwordx4 v[20:21], v[104:107], off offset:896
	global_store_dwordx4 v[20:21], v[108:111], off offset:912
	s_waitcnt vmcnt(22)
	v_lshlrev_b32_e32 v32, 16, v112
	v_lshlrev_b32_e32 v34, 16, v116
	v_and_b32_e32 v35, 0xffff0000, v116
	v_lshlrev_b32_e32 v116, 16, v117
	v_and_b32_e32 v117, 0xffff0000, v117
	v_lshlrev_b32_e32 v38, 16, v118
	v_and_b32_e32 v39, 0xffff0000, v118
	v_lshlrev_b32_e32 v118, 16, v119
	v_and_b32_e32 v119, 0xffff0000, v119
	v_and_b32_e32 v33, 0xffff0000, v112
	v_lshlrev_b32_e32 v112, 16, v113
	v_and_b32_e32 v113, 0xffff0000, v113
	v_lshlrev_b32_e32 v36, 16, v114
	v_and_b32_e32 v37, 0xffff0000, v114
	v_lshlrev_b32_e32 v114, 16, v115
	v_and_b32_e32 v115, 0xffff0000, v115
	v_pk_mul_f32 v[40:41], v[6:7], v[34:35]
	v_pk_mul_f32 v[34:35], v[4:5], v[34:35]
	v_pk_mul_f32 v[42:43], v[10:11], v[116:117]
	v_pk_mul_f32 v[116:117], v[8:9], v[116:117]
	v_pk_mul_f32 v[44:45], v[14:15], v[38:39]
	v_pk_mul_f32 v[38:39], v[12:13], v[38:39]
	v_pk_mul_f32 v[46:47], v[18:19], v[118:119]
	v_pk_mul_f32 v[118:119], v[16:17], v[118:119]
	v_pk_fma_f32 v[40:41], v[4:5], v[32:33], v[40:41]
	v_pk_fma_f32 v[32:33], v[6:7], v[32:33], v[34:35] neg_lo:[0,0,1] neg_hi:[0,0,1]
	v_pk_fma_f32 v[34:35], v[8:9], v[112:113], v[42:43]
	v_pk_fma_f32 v[116:117], v[10:11], v[112:113], v[116:117] neg_lo:[0,0,1] neg_hi:[0,0,1]
	v_pk_fma_f32 v[42:43], v[12:13], v[36:37], v[44:45]
	v_pk_fma_f32 v[36:37], v[14:15], v[36:37], v[38:39] neg_lo:[0,0,1] neg_hi:[0,0,1]
	v_pk_fma_f32 v[118:119], v[18:19], v[114:115], v[118:119] neg_lo:[0,0,1] neg_hi:[0,0,1]
	v_pk_fma_f32 v[38:39], v[16:17], v[114:115], v[46:47]
	v_cvt_pk_bf16_f32 v112, v32, v33
	v_cvt_pk_bf16_f32 v113, v116, v117
	v_cvt_pk_bf16_f32 v114, v36, v37
	v_cvt_pk_bf16_f32 v115, v118, v119
	v_cvt_pk_bf16_f32 v116, v40, v41
	v_cvt_pk_bf16_f32 v117, v34, v35
	v_cvt_pk_bf16_f32 v118, v42, v43
	v_cvt_pk_bf16_f32 v119, v38, v39
	global_store_dwordx4 v[20:21], v[112:115], off offset:1536
	global_store_dwordx4 v[20:21], v[116:119], off offset:1552
	s_waitcnt vmcnt(22)
	v_lshlrev_b32_e32 v32, 16, v120
	v_lshlrev_b32_e32 v34, 16, v124
	v_and_b32_e32 v35, 0xffff0000, v124
	v_lshlrev_b32_e32 v124, 16, v125
	v_and_b32_e32 v125, 0xffff0000, v125
	v_lshlrev_b32_e32 v38, 16, v126
	v_and_b32_e32 v39, 0xffff0000, v126
	v_lshlrev_b32_e32 v126, 16, v127
	v_and_b32_e32 v127, 0xffff0000, v127
	v_and_b32_e32 v33, 0xffff0000, v120
	v_lshlrev_b32_e32 v120, 16, v121
	v_and_b32_e32 v121, 0xffff0000, v121
	v_lshlrev_b32_e32 v36, 16, v122
	v_and_b32_e32 v37, 0xffff0000, v122
	v_lshlrev_b32_e32 v122, 16, v123
	v_and_b32_e32 v123, 0xffff0000, v123
	v_pk_mul_f32 v[40:41], v[6:7], v[34:35]
	v_pk_mul_f32 v[34:35], v[4:5], v[34:35]
	v_pk_mul_f32 v[42:43], v[10:11], v[124:125]
	v_pk_mul_f32 v[124:125], v[8:9], v[124:125]
	v_pk_mul_f32 v[44:45], v[14:15], v[38:39]
	v_pk_mul_f32 v[38:39], v[12:13], v[38:39]
	v_pk_mul_f32 v[46:47], v[18:19], v[126:127]
	v_pk_mul_f32 v[126:127], v[16:17], v[126:127]
	v_pk_fma_f32 v[40:41], v[4:5], v[32:33], v[40:41]
	v_pk_fma_f32 v[32:33], v[6:7], v[32:33], v[34:35] neg_lo:[0,0,1] neg_hi:[0,0,1]
	v_pk_fma_f32 v[34:35], v[8:9], v[120:121], v[42:43]
	v_pk_fma_f32 v[124:125], v[10:11], v[120:121], v[124:125] neg_lo:[0,0,1] neg_hi:[0,0,1]
	v_pk_fma_f32 v[42:43], v[12:13], v[36:37], v[44:45]
	v_pk_fma_f32 v[36:37], v[14:15], v[36:37], v[38:39] neg_lo:[0,0,1] neg_hi:[0,0,1]
	v_pk_fma_f32 v[126:127], v[18:19], v[122:123], v[126:127] neg_lo:[0,0,1] neg_hi:[0,0,1]
	v_pk_fma_f32 v[38:39], v[16:17], v[122:123], v[46:47]
	v_cvt_pk_bf16_f32 v120, v32, v33
	v_cvt_pk_bf16_f32 v121, v124, v125
	v_cvt_pk_bf16_f32 v122, v36, v37
	v_cvt_pk_bf16_f32 v123, v126, v127
	v_cvt_pk_bf16_f32 v124, v40, v41
	v_cvt_pk_bf16_f32 v125, v34, v35
	v_cvt_pk_bf16_f32 v126, v42, v43
	v_cvt_pk_bf16_f32 v127, v38, v39
	global_store_dwordx4 v[20:21], v[120:123], off offset:1664
	global_store_dwordx4 v[20:21], v[124:127], off offset:1680
	s_waitcnt vmcnt(22)
	v_lshlrev_b32_e32 v32, 16, v128
	v_lshlrev_b32_e32 v34, 16, v132
	v_and_b32_e32 v35, 0xffff0000, v132
	v_lshlrev_b32_e32 v132, 16, v133
	v_and_b32_e32 v133, 0xffff0000, v133
	v_lshlrev_b32_e32 v38, 16, v134
	v_and_b32_e32 v39, 0xffff0000, v134
	v_lshlrev_b32_e32 v134, 16, v135
	v_and_b32_e32 v135, 0xffff0000, v135
	v_and_b32_e32 v33, 0xffff0000, v128
	v_lshlrev_b32_e32 v128, 16, v129
	v_and_b32_e32 v129, 0xffff0000, v129
	v_lshlrev_b32_e32 v36, 16, v130
	v_and_b32_e32 v37, 0xffff0000, v130
	v_lshlrev_b32_e32 v130, 16, v131
	v_and_b32_e32 v131, 0xffff0000, v131
	v_pk_mul_f32 v[40:41], v[6:7], v[34:35]
	v_pk_mul_f32 v[34:35], v[4:5], v[34:35]
	v_pk_mul_f32 v[42:43], v[10:11], v[132:133]
	v_pk_mul_f32 v[132:133], v[8:9], v[132:133]
	v_pk_mul_f32 v[44:45], v[14:15], v[38:39]
	v_pk_mul_f32 v[38:39], v[12:13], v[38:39]
	v_pk_mul_f32 v[46:47], v[18:19], v[134:135]
	v_pk_mul_f32 v[134:135], v[16:17], v[134:135]
	v_pk_fma_f32 v[40:41], v[4:5], v[32:33], v[40:41]
	v_pk_fma_f32 v[32:33], v[6:7], v[32:33], v[34:35] neg_lo:[0,0,1] neg_hi:[0,0,1]
	v_pk_fma_f32 v[34:35], v[8:9], v[128:129], v[42:43]
	v_pk_fma_f32 v[132:133], v[10:11], v[128:129], v[132:133] neg_lo:[0,0,1] neg_hi:[0,0,1]
	v_pk_fma_f32 v[42:43], v[12:13], v[36:37], v[44:45]
	v_pk_fma_f32 v[36:37], v[14:15], v[36:37], v[38:39] neg_lo:[0,0,1] neg_hi:[0,0,1]
	v_pk_fma_f32 v[134:135], v[18:19], v[130:131], v[134:135] neg_lo:[0,0,1] neg_hi:[0,0,1]
	v_pk_fma_f32 v[38:39], v[16:17], v[130:131], v[46:47]
	v_cvt_pk_bf16_f32 v128, v32, v33
	v_cvt_pk_bf16_f32 v129, v132, v133
	v_cvt_pk_bf16_f32 v130, v36, v37
	v_cvt_pk_bf16_f32 v131, v134, v135
	v_cvt_pk_bf16_f32 v132, v40, v41
	v_cvt_pk_bf16_f32 v133, v34, v35
	v_cvt_pk_bf16_f32 v134, v42, v43
	v_cvt_pk_bf16_f32 v135, v38, v39
	global_store_dwordx4 v[20:21], v[128:131], off offset:2048
	global_store_dwordx4 v[20:21], v[132:135], off offset:2064
	s_waitcnt vmcnt(22)
	v_lshlrev_b32_e32 v32, 16, v136
	v_lshlrev_b32_e32 v34, 16, v140
	v_and_b32_e32 v35, 0xffff0000, v140
	v_lshlrev_b32_e32 v140, 16, v141
	v_and_b32_e32 v141, 0xffff0000, v141
	v_lshlrev_b32_e32 v38, 16, v142
	v_and_b32_e32 v39, 0xffff0000, v142
	v_lshlrev_b32_e32 v142, 16, v143
	v_and_b32_e32 v143, 0xffff0000, v143
	v_and_b32_e32 v33, 0xffff0000, v136
	v_lshlrev_b32_e32 v136, 16, v137
	v_and_b32_e32 v137, 0xffff0000, v137
	v_lshlrev_b32_e32 v36, 16, v138
	v_and_b32_e32 v37, 0xffff0000, v138
	v_lshlrev_b32_e32 v138, 16, v139
	v_and_b32_e32 v139, 0xffff0000, v139
	v_pk_mul_f32 v[40:41], v[6:7], v[34:35]
	v_pk_mul_f32 v[34:35], v[4:5], v[34:35]
	v_pk_mul_f32 v[42:43], v[10:11], v[140:141]
	v_pk_mul_f32 v[140:141], v[8:9], v[140:141]
	v_pk_mul_f32 v[44:45], v[14:15], v[38:39]
	v_pk_mul_f32 v[38:39], v[12:13], v[38:39]
	v_pk_mul_f32 v[46:47], v[18:19], v[142:143]
	v_pk_mul_f32 v[142:143], v[16:17], v[142:143]
	v_pk_fma_f32 v[40:41], v[4:5], v[32:33], v[40:41]
	v_pk_fma_f32 v[32:33], v[6:7], v[32:33], v[34:35] neg_lo:[0,0,1] neg_hi:[0,0,1]
	v_pk_fma_f32 v[34:35], v[8:9], v[136:137], v[42:43]
	v_pk_fma_f32 v[140:141], v[10:11], v[136:137], v[140:141] neg_lo:[0,0,1] neg_hi:[0,0,1]
	v_pk_fma_f32 v[42:43], v[12:13], v[36:37], v[44:45]
	v_pk_fma_f32 v[36:37], v[14:15], v[36:37], v[38:39] neg_lo:[0,0,1] neg_hi:[0,0,1]
	v_pk_fma_f32 v[142:143], v[18:19], v[138:139], v[142:143] neg_lo:[0,0,1] neg_hi:[0,0,1]
	v_pk_fma_f32 v[38:39], v[16:17], v[138:139], v[46:47]
	v_cvt_pk_bf16_f32 v136, v32, v33
	v_cvt_pk_bf16_f32 v137, v140, v141
	v_cvt_pk_bf16_f32 v138, v36, v37
	v_cvt_pk_bf16_f32 v139, v142, v143
	v_cvt_pk_bf16_f32 v140, v40, v41
	v_cvt_pk_bf16_f32 v141, v34, v35
	v_cvt_pk_bf16_f32 v142, v42, v43
	v_cvt_pk_bf16_f32 v143, v38, v39
	global_store_dwordx4 v[20:21], v[136:139], off offset:2176
	global_store_dwordx4 v[20:21], v[140:143], off offset:2192
	s_branch .LBB0_665
